# static s_setprio 1 for waves 4-7 (younger half) during the mixer loop, reset to 0 at loop exit
# baseline (speedup 1.0000x reference)
; #define GSYNC() do { _Pragma("unroll 1") for (int sy_ = 0; sy_ < PROBE_SYNCREP; ++sy_) xcd_barrier(xbar); } while (0)
; __global__ void __launch_bounds__(NTHR, 2) mega_fwd(Args a) {
;     ...
;                 for (int u = bx; u < 256 + NB * NCH; u += G) {
;                     __syncthreads();
;                     if (u < 256) { _Pragma("unroll 1") for (int rp = 0; rp < PROBE_ATTNREP; ++rp) { attn_unit(a, l, u >> 6, u & 63, lds); __syncthreads(); } }
;                     else { const int v = u - 256; _Pragma("unroll 1") for (int rp = 0; rp < PROBE_D1REP; ++rp) lru_unit<0>(a, l, v / NCH, v % NCH, lds); }
;                 }
;                 GSYNC();
.LBB0_174:
	s_or_b64 exec, exec, s[0:1]
	v_readfirstlane_b32 s28, v226
	s_cmpk_lt_u32 s28, 0x100
	s_cbranch_scc1 .Lmix_prio_done
	s_setprio 1
.Lmix_prio_done:
	v_readlane_b32 s0, v253, 32
	v_readlane_b32 s1, v253, 33
	s_andn2_b64 vcc, exec, s[0:1]
	v_readlane_b32 s64, v254, 25
	s_mov_b32 s65, s2
	s_waitcnt lgkmcnt(0)
	s_barrier
	s_cbranch_vccz .LBB0_180
.LBB0_175:
	s_setprio 0
	s_waitcnt vmcnt(0)
	s_barrier
	s_and_saveexec_b64 s[0:1], s[80:81]
	s_cbranch_execz .LBB0_252
	v_readlane_b32 s4, v254, 27
	s_waitcnt vmcnt(0) expcnt(0) lgkmcnt(0)
	s_nop 0
	v_mov_b32_e32 v0, s4
	ds_read_b32 v3, v0
	v_readlane_b32 s4, v254, 28
	s_waitcnt lgkmcnt(0)
	v_cmp_ne_u32_e32 vcc, 0, v3
	v_mov_b32_e32 v0, s4
	ds_read_b32 v2, v0
	s_cbranch_vccnz .LBB0_216
	s_mov_b32 s42, 1
	s_branch .LBB0_204
